# residual-update epilogues (w_out, ff2): prefetch pairs no longer drained with vmcnt(0); counted waits at first use
# baseline (speedup 1.0000x reference)
; __device__ __forceinline__ float bflo(unsigned u) { return __uint_as_float(u << 16); }
; __device__ __forceinline__ float bfhi(unsigned u) { return __uint_as_float(u & 0xffff0000u); }
;     __device__ __forceinline__ void operator()(const Acc& acc, const Unit& u, int wr, int wc, int fr, int fq) const {
;     ...
;         u32x4 hb[2][2];
; #pragma unroll
;         for (int bj = 0; bj < 2; ++bj) hb[0][bj] = *(const u32x4*)(Hin + (size_t)row0 * 1024 + col0 + bj * HALF);
; #pragma unroll
;         for (int it = 0; it < 8; ++it) { const int ai = it >> 2, m = it & 3; const int row = row0 + ai * HALF + m * 16; float s = 0.f;
;             if (it + 1 < 8) { const bf16_t* np = Hin + (size_t)(row0 + ((it + 1) >> 2) * HALF + ((it + 1) & 3) * 16) * 1024 + col0;
; #pragma unroll
;                 for (int bj = 0; bj < 2; ++bj) hb[(it + 1) & 1][bj] = *(const u32x4*)(np + bj * HALF); }
; #pragma unroll
;             for (int bj = 0; bj < 2; ++bj) { const u32x4 hv = hb[it & 1][bj];
;                 f32x4 o0 = acc[ai][bj][m][0] * sc, o1 = acc[ai][bj][m][1] * sc;
;                 o0[0] += bflo(hv.x); o0[1] += bfhi(hv.x); o0[2] += bflo(hv.y); o0[3] += bfhi(hv.y); o1[0] += bflo(hv.z); o1[1] += bfhi(hv.z); o1[2] += bflo(hv.w); o1[3] += bfhi(hv.w);
;                 s += ((o0[0] * o0[0] + o0[1] * o0[1]) + (o0[2] * o0[2] + o0[3] * o0[3])) + ((o1[0] * o1[0] + o1[1] * o1[1]) + (o1[2] * o1[2] + o1[3] * o1[3]));
;                 if (Xout) { float* xp = Xout + (size_t)row * 1024 + col0 + bj * HALF; *(f32x4*)xp = o0; *(f32x4*)(xp + 4) = o1; }
.LBB0_105:
	s_lshl_b32 s0, s40, 8
	v_mov_b32_e32 v168, v165
	v_mov_b32_e32 v130, v164
	s_add_i32 s0, s0, s47
	v_cndmask_b32_e64 v169, 0, 1, s[82:83]
	v_add_u32_e32 v154, s0, v130
	s_lshl_b32 s0, s92, 8
	s_or_b32 s0, s0, s65
	v_lshl_add_u32 v152, v168, 3, s0
	v_ashrrev_i32_e32 v155, 31, v154
	v_lshlrev_b64 v[160:161], 11, v[154:155]
	v_ashrrev_i32_e32 v153, 31, v152
	v_lshl_add_u64 v[130:131], s[36:37], 0, v[160:161]
	v_lshlrev_b64 v[132:133], 1, v[152:153]
	v_add_u32_e32 v156, 16, v154
	v_lshl_add_u64 v[130:131], v[130:131], 0, v[132:133]
	v_ashrrev_i32_e32 v157, 31, v156
	global_load_dwordx4 v[170:173], v[130:131], off
	global_load_dwordx4 v[138:141], v[130:131], off offset:256
	v_lshlrev_b64 v[158:159], 11, v[156:157]
	v_lshl_add_u64 v[130:131], s[36:37], 0, v[158:159]
	v_lshl_add_u64 v[130:131], v[130:131], 0, v[132:133]
	global_load_dwordx4 v[134:137], v[130:131], off
	s_nop 0
	global_load_dwordx4 v[130:133], v[130:131], off offset:256
	v_lshlrev_b64 v[162:163], 12, v[154:155]
	v_lshl_add_u64 v[162:163], s[58:59], 0, v[162:163]
	v_cmp_ne_u32_e64 s[40:41], 1, v169
	s_andn2_b64 vcc, exec, s[82:83]
	v_lshl_add_u64 v[162:163], v[152:153], 2, v[162:163]
	s_waitcnt vmcnt(2) lgkmcnt(0)
	v_lshlrev_b32_e32 v174, 16, v170
	v_and_b32_e32 v175, 0xffff0000, v170
	v_lshlrev_b32_e32 v170, 16, v171
	v_and_b32_e32 v171, 0xffff0000, v171
	v_pk_add_f32 v[128:129], v[128:129], v[170:171]
	v_lshlrev_b32_e32 v170, 16, v172
	v_and_b32_e32 v171, 0xffff0000, v172
	v_pk_add_f32 v[122:123], v[122:123], v[170:171]
	v_lshlrev_b32_e32 v170, 16, v173
	v_and_b32_e32 v171, 0xffff0000, v173
	v_pk_add_f32 v[126:127], v[126:127], v[174:175]
	v_pk_add_f32 v[124:125], v[124:125], v[170:171]
	s_cbranch_vccnz .LBB0_172
	global_store_dwordx4 v[162:163], v[126:129], off
	global_store_dwordx4 v[162:163], v[122:125], off offset:16
	s_cbranch_execnz .LBB0_108

; __device__ __forceinline__ float bflo(unsigned u) { return __uint_as_float(u << 16); }
; __device__ __forceinline__ float bfhi(unsigned u) { return __uint_as_float(u & 0xffff0000u); }
;     __device__ __forceinline__ void operator()(const Acc& acc, const Unit& u, int wr, int wc, int fr, int fq) const {
;     ...
;         for (int it = 0; it < 8; ++it) { const int ai = it >> 2, m = it & 3; const int row = row0 + ai * HALF + m * 16; float s = 0.f;
;             if (it + 1 < 8) { const bf16_t* np = Hin + (size_t)(row0 + ((it + 1) >> 2) * HALF + ((it + 1) & 3) * 16) * 1024 + col0;
; #pragma unroll
;                 for (int bj = 0; bj < 2; ++bj) hb[(it + 1) & 1][bj] = *(const u32x4*)(np + bj * HALF); }
; #pragma unroll
;             for (int bj = 0; bj < 2; ++bj) { const u32x4 hv = hb[it & 1][bj];
;                 f32x4 o0 = acc[ai][bj][m][0] * sc, o1 = acc[ai][bj][m][1] * sc;
;                 o0[0] += bflo(hv.x); o0[1] += bfhi(hv.x); o0[2] += bflo(hv.y); o0[3] += bfhi(hv.y); o1[0] += bflo(hv.z); o1[1] += bfhi(hv.z); o1[2] += bflo(hv.w); o1[3] += bfhi(hv.w);
;                 s += ((o0[0] * o0[0] + o0[1] * o0[1]) + (o0[2] * o0[2] + o0[3] * o0[3])) + ((o1[0] * o1[0] + o1[1] * o1[1]) + (o1[2] * o1[2] + o1[3] * o1[3]));
;                 if (Xout) { float* xp = Xout + (size_t)row * 1024 + col0 + bj * HALF; *(f32x4*)xp = o0; *(f32x4*)(xp + 4) = o1; }
.LBB0_113:
	s_or_b64 exec, exec, s[0:1]
	v_add_u32_e32 v122, 32, v154
	v_ashrrev_i32_e32 v123, 31, v122
	v_lshlrev_b64 v[124:125], 11, v[122:123]
	s_waitcnt lgkmcnt(0)
	v_lshl_add_u64 v[114:115], s[36:37], 0, v[124:125]
	v_lshl_add_u64 v[114:115], v[152:153], 1, v[114:115]
	global_load_dwordx4 v[118:121], v[114:115], off
	s_nop 0
	global_load_dwordx4 v[114:117], v[114:115], off offset:256
	s_waitcnt vmcnt(5)
	v_lshlrev_b32_e32 v138, 16, v134
	v_and_b32_e32 v139, 0xffff0000, v134
	v_lshlrev_b32_e32 v134, 16, v135
	v_and_b32_e32 v135, 0xffff0000, v135
	v_lshlrev_b64 v[126:127], 12, v[156:157]
	v_pk_add_f32 v[112:113], v[112:113], v[134:135]
	v_lshlrev_b32_e32 v134, 16, v136
	v_and_b32_e32 v135, 0xffff0000, v136
	v_pk_add_f32 v[106:107], v[106:107], v[134:135]
	v_lshlrev_b32_e32 v134, 16, v137
	v_and_b32_e32 v135, 0xffff0000, v137
	v_lshl_add_u64 v[126:127], s[58:59], 0, v[126:127]
	v_pk_add_f32 v[110:111], v[110:111], v[138:139]
	v_pk_add_f32 v[108:109], v[108:109], v[134:135]
	s_and_b64 vcc, exec, s[40:41]
	v_lshl_add_u64 v[126:127], v[152:153], 2, v[126:127]
	s_cbranch_vccnz .LBB0_174
	global_store_dwordx4 v[126:127], v[110:113], off
	global_store_dwordx4 v[126:127], v[106:109], off offset:16
	s_cbranch_execnz .LBB0_116

; __device__ __forceinline__ float bflo(unsigned u) { return __uint_as_float(u << 16); }
; __device__ __forceinline__ float bfhi(unsigned u) { return __uint_as_float(u & 0xffff0000u); }
;     __device__ __forceinline__ void operator()(const Acc& acc, const Unit& u, int wr, int wc, int fr, int fq) const {
;     ...
;         for (int it = 0; it < 8; ++it) { const int ai = it >> 2, m = it & 3; const int row = row0 + ai * HALF + m * 16; float s = 0.f;
;             if (it + 1 < 8) { const bf16_t* np = Hin + (size_t)(row0 + ((it + 1) >> 2) * HALF + ((it + 1) & 3) * 16) * 1024 + col0;
; #pragma unroll
;                 for (int bj = 0; bj < 2; ++bj) hb[(it + 1) & 1][bj] = *(const u32x4*)(np + bj * HALF); }
; #pragma unroll
;             for (int bj = 0; bj < 2; ++bj) { const u32x4 hv = hb[it & 1][bj];
;                 f32x4 o0 = acc[ai][bj][m][0] * sc, o1 = acc[ai][bj][m][1] * sc;
;                 o0[0] += bflo(hv.x); o0[1] += bfhi(hv.x); o0[2] += bflo(hv.y); o0[3] += bfhi(hv.y); o1[0] += bflo(hv.z); o1[1] += bfhi(hv.z); o1[2] += bflo(hv.w); o1[3] += bfhi(hv.w);
;                 s += ((o0[0] * o0[0] + o0[1] * o0[1]) + (o0[2] * o0[2] + o0[3] * o0[3])) + ((o1[0] * o1[0] + o1[1] * o1[1]) + (o1[2] * o1[2] + o1[3] * o1[3]));
;                 if (Xout) { float* xp = Xout + (size_t)row * 1024 + col0 + bj * HALF; *(f32x4*)xp = o0; *(f32x4*)(xp + 4) = o1; }
.LBB0_121:
	s_or_b64 exec, exec, s[0:1]
	v_add_u32_e32 v106, 48, v154
	v_ashrrev_i32_e32 v107, 31, v106
	v_lshlrev_b64 v[108:109], 11, v[106:107]
	s_waitcnt lgkmcnt(0)
	v_lshl_add_u64 v[98:99], s[36:37], 0, v[108:109]
	v_lshl_add_u64 v[98:99], v[152:153], 1, v[98:99]
	global_load_dwordx4 v[102:105], v[98:99], off
	s_nop 0
	global_load_dwordx4 v[98:101], v[98:99], off offset:256
	s_waitcnt vmcnt(2)
	v_lshlrev_b32_e32 v112, 16, v118
	v_and_b32_e32 v113, 0xffff0000, v118
	v_pk_add_f32 v[94:95], v[94:95], v[112:113]
	v_lshlrev_b32_e32 v112, 16, v119
	v_and_b32_e32 v113, 0xffff0000, v119
	v_lshlrev_b64 v[110:111], 12, v[122:123]
	v_pk_add_f32 v[96:97], v[96:97], v[112:113]
	v_lshlrev_b32_e32 v112, 16, v120
	v_and_b32_e32 v113, 0xffff0000, v120
	v_pk_add_f32 v[90:91], v[90:91], v[112:113]
	v_lshlrev_b32_e32 v112, 16, v121
	v_and_b32_e32 v113, 0xffff0000, v121
	v_lshl_add_u64 v[110:111], s[58:59], 0, v[110:111]
	v_pk_add_f32 v[92:93], v[92:93], v[112:113]
	s_and_b64 vcc, exec, s[40:41]
	v_lshl_add_u64 v[110:111], v[152:153], 2, v[110:111]
	s_cbranch_vccnz .LBB0_176
	global_store_dwordx4 v[110:111], v[94:97], off
	global_store_dwordx4 v[110:111], v[90:93], off offset:16
	s_cbranch_execnz .LBB0_124

; __device__ __forceinline__ float bflo(unsigned u) { return __uint_as_float(u << 16); }
; __device__ __forceinline__ float bfhi(unsigned u) { return __uint_as_float(u & 0xffff0000u); }
;     __device__ __forceinline__ void operator()(const Acc& acc, const Unit& u, int wr, int wc, int fr, int fq) const {
;     ...
;         for (int it = 0; it < 8; ++it) { const int ai = it >> 2, m = it & 3; const int row = row0 + ai * HALF + m * 16; float s = 0.f;
;             if (it + 1 < 8) { const bf16_t* np = Hin + (size_t)(row0 + ((it + 1) >> 2) * HALF + ((it + 1) & 3) * 16) * 1024 + col0;
; #pragma unroll
;                 for (int bj = 0; bj < 2; ++bj) hb[(it + 1) & 1][bj] = *(const u32x4*)(np + bj * HALF); }
; #pragma unroll
;             for (int bj = 0; bj < 2; ++bj) { const u32x4 hv = hb[it & 1][bj];
;                 f32x4 o0 = acc[ai][bj][m][0] * sc, o1 = acc[ai][bj][m][1] * sc;
;                 o0[0] += bflo(hv.x); o0[1] += bfhi(hv.x); o0[2] += bflo(hv.y); o0[3] += bfhi(hv.y); o1[0] += bflo(hv.z); o1[1] += bfhi(hv.z); o1[2] += bflo(hv.w); o1[3] += bfhi(hv.w);
;                 s += ((o0[0] * o0[0] + o0[1] * o0[1]) + (o0[2] * o0[2] + o0[3] * o0[3])) + ((o1[0] * o1[0] + o1[1] * o1[1]) + (o1[2] * o1[2] + o1[3] * o1[3]));
;                 if (Xout) { float* xp = Xout + (size_t)row * 1024 + col0 + bj * HALF; *(f32x4*)xp = o0; *(f32x4*)(xp + 4) = o1; }
.LBB0_129:
	s_or_b64 exec, exec, s[0:1]
	v_add_u32_e32 v90, 0x80, v154
	v_ashrrev_i32_e32 v91, 31, v90
	v_lshlrev_b64 v[92:93], 11, v[90:91]
	s_waitcnt lgkmcnt(0)
	v_lshl_add_u64 v[82:83], s[36:37], 0, v[92:93]
	v_lshl_add_u64 v[82:83], v[152:153], 1, v[82:83]
	global_load_dwordx4 v[86:89], v[82:83], off
	s_nop 0
	global_load_dwordx4 v[82:85], v[82:83], off offset:256
	s_waitcnt vmcnt(5)
	v_lshlrev_b32_e32 v96, 16, v102
	v_and_b32_e32 v97, 0xffff0000, v102
	v_pk_add_f32 v[78:79], v[78:79], v[96:97]
	v_lshlrev_b32_e32 v96, 16, v103
	v_and_b32_e32 v97, 0xffff0000, v103
	v_lshlrev_b64 v[94:95], 12, v[106:107]
	v_pk_add_f32 v[80:81], v[80:81], v[96:97]
	v_lshlrev_b32_e32 v96, 16, v104
	v_and_b32_e32 v97, 0xffff0000, v104
	v_pk_add_f32 v[74:75], v[74:75], v[96:97]
	v_lshlrev_b32_e32 v96, 16, v105
	v_and_b32_e32 v97, 0xffff0000, v105
	v_lshl_add_u64 v[94:95], s[58:59], 0, v[94:95]
	v_pk_add_f32 v[76:77], v[76:77], v[96:97]
	s_and_b64 vcc, exec, s[40:41]
	v_lshl_add_u64 v[94:95], v[152:153], 2, v[94:95]
	s_cbranch_vccnz .LBB0_178
	global_store_dwordx4 v[94:95], v[78:81], off
	global_store_dwordx4 v[94:95], v[74:77], off offset:16
	s_cbranch_execnz .LBB0_132

; __device__ __forceinline__ float bflo(unsigned u) { return __uint_as_float(u << 16); }
; __device__ __forceinline__ float bfhi(unsigned u) { return __uint_as_float(u & 0xffff0000u); }
;     __device__ __forceinline__ void operator()(const Acc& acc, const Unit& u, int wr, int wc, int fr, int fq) const {
;     ...
;         for (int it = 0; it < 8; ++it) { const int ai = it >> 2, m = it & 3; const int row = row0 + ai * HALF + m * 16; float s = 0.f;
;             if (it + 1 < 8) { const bf16_t* np = Hin + (size_t)(row0 + ((it + 1) >> 2) * HALF + ((it + 1) & 3) * 16) * 1024 + col0;
; #pragma unroll
;                 for (int bj = 0; bj < 2; ++bj) hb[(it + 1) & 1][bj] = *(const u32x4*)(np + bj * HALF); }
; #pragma unroll
;             for (int bj = 0; bj < 2; ++bj) { const u32x4 hv = hb[it & 1][bj];
;                 f32x4 o0 = acc[ai][bj][m][0] * sc, o1 = acc[ai][bj][m][1] * sc;
;                 o0[0] += bflo(hv.x); o0[1] += bfhi(hv.x); o0[2] += bflo(hv.y); o0[3] += bfhi(hv.y); o1[0] += bflo(hv.z); o1[1] += bfhi(hv.z); o1[2] += bflo(hv.w); o1[3] += bfhi(hv.w);
;                 s += ((o0[0] * o0[0] + o0[1] * o0[1]) + (o0[2] * o0[2] + o0[3] * o0[3])) + ((o1[0] * o1[0] + o1[1] * o1[1]) + (o1[2] * o1[2] + o1[3] * o1[3]));
;                 if (Xout) { float* xp = Xout + (size_t)row * 1024 + col0 + bj * HALF; *(f32x4*)xp = o0; *(f32x4*)(xp + 4) = o1; }
.LBB0_137:
	s_or_b64 exec, exec, s[0:1]
	v_add_u32_e32 v74, 0x90, v154
	v_ashrrev_i32_e32 v75, 31, v74
	v_lshlrev_b64 v[76:77], 11, v[74:75]
	s_waitcnt lgkmcnt(0)
	v_lshl_add_u64 v[66:67], s[36:37], 0, v[76:77]
	v_lshl_add_u64 v[66:67], v[152:153], 1, v[66:67]
	global_load_dwordx4 v[70:73], v[66:67], off
	s_nop 0
	global_load_dwordx4 v[66:69], v[66:67], off offset:256
	s_waitcnt vmcnt(2)
	v_lshlrev_b32_e32 v80, 16, v86
	v_and_b32_e32 v81, 0xffff0000, v86
	v_pk_add_f32 v[62:63], v[62:63], v[80:81]
	v_lshlrev_b32_e32 v80, 16, v87
	v_and_b32_e32 v81, 0xffff0000, v87
	v_lshlrev_b64 v[78:79], 12, v[90:91]
	v_pk_add_f32 v[64:65], v[64:65], v[80:81]
	v_lshlrev_b32_e32 v80, 16, v88
	v_and_b32_e32 v81, 0xffff0000, v88
	v_pk_add_f32 v[58:59], v[58:59], v[80:81]
	v_lshlrev_b32_e32 v80, 16, v89
	v_and_b32_e32 v81, 0xffff0000, v89
	v_lshl_add_u64 v[78:79], s[58:59], 0, v[78:79]
	v_pk_add_f32 v[60:61], v[60:61], v[80:81]
	s_and_b64 vcc, exec, s[40:41]
	v_lshl_add_u64 v[78:79], v[152:153], 2, v[78:79]
	s_cbranch_vccnz .LBB0_180
	global_store_dwordx4 v[78:79], v[62:65], off
	global_store_dwordx4 v[78:79], v[58:61], off offset:16
	s_cbranch_execnz .LBB0_140

; __device__ __forceinline__ float bflo(unsigned u) { return __uint_as_float(u << 16); }
; __device__ __forceinline__ float bfhi(unsigned u) { return __uint_as_float(u & 0xffff0000u); }
;     __device__ __forceinline__ void operator()(const Acc& acc, const Unit& u, int wr, int wc, int fr, int fq) const {
;     ...
;         for (int it = 0; it < 8; ++it) { const int ai = it >> 2, m = it & 3; const int row = row0 + ai * HALF + m * 16; float s = 0.f;
;             if (it + 1 < 8) { const bf16_t* np = Hin + (size_t)(row0 + ((it + 1) >> 2) * HALF + ((it + 1) & 3) * 16) * 1024 + col0;
; #pragma unroll
;                 for (int bj = 0; bj < 2; ++bj) hb[(it + 1) & 1][bj] = *(const u32x4*)(np + bj * HALF); }
; #pragma unroll
;             for (int bj = 0; bj < 2; ++bj) { const u32x4 hv = hb[it & 1][bj];
;                 f32x4 o0 = acc[ai][bj][m][0] * sc, o1 = acc[ai][bj][m][1] * sc;
;                 o0[0] += bflo(hv.x); o0[1] += bfhi(hv.x); o0[2] += bflo(hv.y); o0[3] += bfhi(hv.y); o1[0] += bflo(hv.z); o1[1] += bfhi(hv.z); o1[2] += bflo(hv.w); o1[3] += bfhi(hv.w);
;                 s += ((o0[0] * o0[0] + o0[1] * o0[1]) + (o0[2] * o0[2] + o0[3] * o0[3])) + ((o1[0] * o1[0] + o1[1] * o1[1]) + (o1[2] * o1[2] + o1[3] * o1[3]));
;                 if (Xout) { float* xp = Xout + (size_t)row * 1024 + col0 + bj * HALF; *(f32x4*)xp = o0; *(f32x4*)(xp + 4) = o1; }
.LBB0_145:
	s_or_b64 exec, exec, s[0:1]
	v_add_u32_e32 v58, 0xa0, v154
	v_ashrrev_i32_e32 v59, 31, v58
	v_lshlrev_b64 v[60:61], 11, v[58:59]
	s_waitcnt lgkmcnt(0)
	v_lshl_add_u64 v[50:51], s[36:37], 0, v[60:61]
	v_lshl_add_u64 v[50:51], v[152:153], 1, v[50:51]
	global_load_dwordx4 v[54:57], v[50:51], off
	s_nop 0
	global_load_dwordx4 v[50:53], v[50:51], off offset:256
	s_waitcnt vmcnt(5)
	v_lshlrev_b32_e32 v64, 16, v70
	v_and_b32_e32 v65, 0xffff0000, v70
	v_pk_add_f32 v[46:47], v[46:47], v[64:65]
	v_lshlrev_b32_e32 v64, 16, v71
	v_and_b32_e32 v65, 0xffff0000, v71
	v_lshlrev_b64 v[62:63], 12, v[74:75]
	v_pk_add_f32 v[48:49], v[48:49], v[64:65]
	v_lshlrev_b32_e32 v64, 16, v72
	v_and_b32_e32 v65, 0xffff0000, v72
	v_pk_add_f32 v[42:43], v[42:43], v[64:65]
	v_lshlrev_b32_e32 v64, 16, v73
	v_and_b32_e32 v65, 0xffff0000, v73
	v_lshl_add_u64 v[62:63], s[58:59], 0, v[62:63]
	v_pk_add_f32 v[44:45], v[44:45], v[64:65]
	s_and_b64 vcc, exec, s[40:41]
	v_lshl_add_u64 v[62:63], v[152:153], 2, v[62:63]
	s_cbranch_vccnz .LBB0_182
	global_store_dwordx4 v[62:63], v[46:49], off
	global_store_dwordx4 v[62:63], v[42:45], off offset:16
	s_cbranch_execnz .LBB0_148

; __device__ __forceinline__ float bflo(unsigned u) { return __uint_as_float(u << 16); }
; __device__ __forceinline__ float bfhi(unsigned u) { return __uint_as_float(u & 0xffff0000u); }
;     __device__ __forceinline__ void operator()(const Acc& acc, const Unit& u, int wr, int wc, int fr, int fq) const {
;     ...
;         for (int it = 0; it < 8; ++it) { const int ai = it >> 2, m = it & 3; const int row = row0 + ai * HALF + m * 16; float s = 0.f;
;             if (it + 1 < 8) { const bf16_t* np = Hin + (size_t)(row0 + ((it + 1) >> 2) * HALF + ((it + 1) & 3) * 16) * 1024 + col0;
; #pragma unroll
;                 for (int bj = 0; bj < 2; ++bj) hb[(it + 1) & 1][bj] = *(const u32x4*)(np + bj * HALF); }
; #pragma unroll
;             for (int bj = 0; bj < 2; ++bj) { const u32x4 hv = hb[it & 1][bj];
;                 f32x4 o0 = acc[ai][bj][m][0] * sc, o1 = acc[ai][bj][m][1] * sc;
;                 o0[0] += bflo(hv.x); o0[1] += bfhi(hv.x); o0[2] += bflo(hv.y); o0[3] += bfhi(hv.y); o1[0] += bflo(hv.z); o1[1] += bfhi(hv.z); o1[2] += bflo(hv.w); o1[3] += bfhi(hv.w);
;                 s += ((o0[0] * o0[0] + o0[1] * o0[1]) + (o0[2] * o0[2] + o0[3] * o0[3])) + ((o1[0] * o1[0] + o1[1] * o1[1]) + (o1[2] * o1[2] + o1[3] * o1[3]));
;                 if (Xout) { float* xp = Xout + (size_t)row * 1024 + col0 + bj * HALF; *(f32x4*)xp = o0; *(f32x4*)(xp + 4) = o1; }
.LBB0_153:
	s_or_b64 exec, exec, s[0:1]
	v_add_u32_e32 v42, 0xb0, v154
	v_ashrrev_i32_e32 v43, 31, v42
	v_lshlrev_b64 v[44:45], 11, v[42:43]
	s_waitcnt lgkmcnt(0)
	v_lshl_add_u64 v[34:35], s[36:37], 0, v[44:45]
	v_lshl_add_u64 v[34:35], v[152:153], 1, v[34:35]
	global_load_dwordx4 v[38:41], v[34:35], off
	s_nop 0
	global_load_dwordx4 v[34:37], v[34:35], off offset:256
	s_waitcnt vmcnt(2)
	v_lshlrev_b32_e32 v48, 16, v54
	v_and_b32_e32 v49, 0xffff0000, v54
	v_pk_add_f32 v[30:31], v[30:31], v[48:49]
	v_lshlrev_b32_e32 v48, 16, v55
	v_and_b32_e32 v49, 0xffff0000, v55
	v_lshlrev_b64 v[46:47], 12, v[58:59]
	v_pk_add_f32 v[32:33], v[32:33], v[48:49]
	v_lshlrev_b32_e32 v48, 16, v56
	v_and_b32_e32 v49, 0xffff0000, v56
	v_pk_add_f32 v[26:27], v[26:27], v[48:49]
	v_lshlrev_b32_e32 v48, 16, v57
	v_and_b32_e32 v49, 0xffff0000, v57
	v_lshl_add_u64 v[46:47], s[58:59], 0, v[46:47]
	v_pk_add_f32 v[28:29], v[28:29], v[48:49]
	s_and_b64 vcc, exec, s[40:41]
	v_lshl_add_u64 v[46:47], v[152:153], 2, v[46:47]
	s_cbranch_vccnz .LBB0_184
	global_store_dwordx4 v[46:47], v[30:33], off
	global_store_dwordx4 v[46:47], v[26:29], off offset:16
	s_cbranch_execnz .LBB0_156

; __device__ __forceinline__ float bflo(unsigned u) { return __uint_as_float(u << 16); }
; __device__ __forceinline__ float bfhi(unsigned u) { return __uint_as_float(u & 0xffff0000u); }
;     __device__ __forceinline__ void operator()(const Acc& acc, const Unit& u, int wr, int wc, int fr, int fq) const {
;     ...
;             for (int bj = 0; bj < 2; ++bj) { const u32x4 hv = hb[it & 1][bj];
;                 f32x4 o0 = acc[ai][bj][m][0] * sc, o1 = acc[ai][bj][m][1] * sc;
;                 o0[0] += bflo(hv.x); o0[1] += bfhi(hv.x); o0[2] += bflo(hv.y); o0[3] += bfhi(hv.y); o1[0] += bflo(hv.z); o1[1] += bfhi(hv.z); o1[2] += bflo(hv.w); o1[3] += bfhi(hv.w);
;                 s += ((o0[0] * o0[0] + o0[1] * o0[1]) + (o0[2] * o0[2] + o0[3] * o0[3])) + ((o1[0] * o1[0] + o1[1] * o1[1]) + (o1[2] * o1[2] + o1[3] * o1[3]));
;                 if (Xout) { float* xp = Xout + (size_t)row * 1024 + col0 + bj * HALF; *(f32x4*)xp = o0; *(f32x4*)(xp + 4) = o1; }
.LBB0_161:
	s_or_b64 exec, exec, s[0:1]
	s_waitcnt vmcnt(3)
	v_lshlrev_b32_e32 v20, 16, v38
	v_and_b32_e32 v21, 0xffff0000, v38
	v_pk_add_f32 v[14:15], v[14:15], v[20:21]
	v_lshlrev_b32_e32 v20, 16, v39
	v_and_b32_e32 v21, 0xffff0000, v39
	s_waitcnt lgkmcnt(0)
	v_lshlrev_b64 v[18:19], 12, v[42:43]
	v_pk_add_f32 v[16:17], v[16:17], v[20:21]
	v_lshlrev_b32_e32 v20, 16, v40
	v_and_b32_e32 v21, 0xffff0000, v40
	v_pk_add_f32 v[10:11], v[10:11], v[20:21]
	v_lshlrev_b32_e32 v20, 16, v41
	v_and_b32_e32 v21, 0xffff0000, v41
	v_lshl_add_u64 v[18:19], s[58:59], 0, v[18:19]
	v_pk_add_f32 v[12:13], v[12:13], v[20:21]
	s_and_b64 vcc, exec, s[40:41]
	v_lshl_add_u64 v[18:19], v[152:153], 2, v[18:19]
	s_cbranch_vccnz .LBB0_186
	global_store_dwordx4 v[18:19], v[14:17], off
	global_store_dwordx4 v[18:19], v[10:13], off offset:16
	s_cbranch_execnz .LBB0_164

; __device__ __forceinline__ unsigned pk2(float lo, float hi) { f32x2 v = {lo, hi}; bf16x2_t b = __builtin_convertvector(v, bf16x2_t); return __builtin_bit_cast(unsigned, b); }
; __device__ __forceinline__ float bflo(unsigned u) { return __uint_as_float(u << 16); }
; __device__ __forceinline__ float bfhi(unsigned u) { return __uint_as_float(u & 0xffff0000u); }
;     __device__ __forceinline__ void operator()(const Acc& acc, const Unit& u, int wr, int wc, int fr, int fq) const {
;         const int row0 = u.pm * BM + wr * 64 + fr, col0 = u.pn * BM + wc * 32 + 8 * fq;
;         u32x4 hb[2][2];
; #pragma unroll
;         for (int bj = 0; bj < 2; ++bj) hb[0][bj] = *(const u32x4*)(Hin + (size_t)row0 * 1024 + col0 + bj * HALF);
; #pragma unroll
;         for (int it = 0; it < 8; ++it) { const int ai = it >> 2, m = it & 3; const int row = row0 + ai * HALF + m * 16; float s = 0.f;
;             if (it + 1 < 8) { const bf16_t* np = Hin + (size_t)(row0 + ((it + 1) >> 2) * HALF + ((it + 1) & 3) * 16) * 1024 + col0;
; #pragma unroll
;                 for (int bj = 0; bj < 2; ++bj) hb[(it + 1) & 1][bj] = *(const u32x4*)(np + bj * HALF); }
; #pragma unroll
;             for (int bj = 0; bj < 2; ++bj) { const u32x4 hv = hb[it & 1][bj];
;                 f32x4 o0 = acc[ai][bj][m][0] * sc, o1 = acc[ai][bj][m][1] * sc;
;                 o0[0] += bflo(hv.x); o0[1] += bfhi(hv.x); o0[2] += bflo(hv.y); o0[3] += bfhi(hv.y); o1[0] += bflo(hv.z); o1[1] += bfhi(hv.z); o1[2] += bflo(hv.w); o1[3] += bfhi(hv.w);
;                 s += ((o0[0] * o0[0] + o0[1] * o0[1]) + (o0[2] * o0[2] + o0[3] * o0[3])) + ((o1[0] * o1[0] + o1[1] * o1[1]) + (o1[2] * o1[2] + o1[3] * o1[3]));
;                 if (Xout) { float* xp = Xout + (size_t)row * 1024 + col0 + bj * HALF; *(f32x4*)xp = o0; *(f32x4*)(xp + 4) = o1; }
;                 else { u32x4 w; w.x = pk2(o0[0], o0[1]); w.y = pk2(o0[2], o0[3]); w.z = pk2(o1[0], o1[1]); w.w = pk2(o1[2], o1[3]); *(u32x4*)(H + (size_t)row * 1024 + col0 + bj * HALF) = w; } }
;             s += __shfl_xor(s, 16); s += __shfl_xor(s, 32);
;             if (fq == 0) ssq[(size_t)row * 16 + u.pn * 4 + wc] = s;
;             asm volatile("" ::: "memory"); }
.LBB0_241:
	s_lshl_b32 s0, s86, 8
	v_mov_b32_e32 v130, v162
	v_mov_b32_e32 v132, v163
	s_add_i32 s0, s0, s47
	s_nop 0
	v_add_u32_e32 v156, s0, v130
	s_lshl_b32 s0, s84, 8
	s_or_b32 s0, s0, s65
	v_lshl_add_u32 v152, v132, 3, s0
	v_ashrrev_i32_e32 v157, 31, v156
	v_lshlrev_b64 v[172:173], 11, v[156:157]
	v_ashrrev_i32_e32 v153, 31, v152
	v_lshl_add_u64 v[130:131], s[28:29], 0, v[172:173]
	v_lshlrev_b64 v[154:155], 1, v[152:153]
	v_lshl_add_u64 v[130:131], v[130:131], 0, v[154:155]
	global_load_dwordx4 v[168:171], v[130:131], off
	global_load_dwordx4 v[138:141], v[130:131], off offset:256
	v_and_b32_e32 v131, 64, v224
	v_xor_b32_e32 v130, 16, v224
	v_add_u32_e32 v131, 64, v131
	v_cmp_lt_i32_e32 vcc, v130, v131
	v_add_u32_e32 v158, 16, v156
	v_ashrrev_i32_e32 v159, 31, v158
	v_cndmask_b32_e32 v130, v224, v130, vcc
	v_lshlrev_b32_e32 v167, 2, v130
	v_xor_b32_e32 v130, 32, v224
	v_cmp_lt_i32_e32 vcc, v130, v131
	v_lshlrev_b64 v[160:161], 11, v[158:159]
	s_lshl_b32 s84, s84, 2
	v_cndmask_b32_e32 v130, v224, v130, vcc
	v_lshlrev_b32_e32 v166, 2, v130
	v_lshl_add_u64 v[130:131], s[28:29], 0, v[160:161]
	v_lshl_add_u64 v[130:131], v[130:131], 0, v[154:155]
	v_cmp_eq_u32_e32 vcc, 0, v132
	global_load_dwordx4 v[134:137], v[130:131], off
	s_nop 0
	global_load_dwordx4 v[130:133], v[130:131], off offset:256
	s_ashr_i32 s85, s84, 31
	s_waitcnt vmcnt(2) lgkmcnt(0)
	v_lshlrev_b32_e32 v174, 16, v168
	v_and_b32_e32 v175, 0xffff0000, v168
	v_lshlrev_b32_e32 v168, 16, v169
	v_and_b32_e32 v169, 0xffff0000, v169
	v_pk_add_f32 v[128:129], v[128:129], v[168:169]
	v_lshlrev_b32_e32 v168, 16, v170
	v_and_b32_e32 v169, 0xffff0000, v170
	v_pk_add_f32 v[126:127], v[126:127], v[174:175]
	v_pk_add_f32 v[168:169], v[122:123], v[168:169]
	v_lshlrev_b32_e32 v122, 16, v171
	v_and_b32_e32 v123, 0xffff0000, v171
	v_pk_add_f32 v[170:171], v[124:125], v[122:123]
	v_pk_mul_f32 v[174:175], v[126:127], v[126:127]
	v_cvt_pk_bf16_f32 v122, v126, v127
	v_lshl_add_u64 v[126:127], s[36:37], 0, v[172:173]
	v_cvt_pk_bf16_f32 v123, v128, v129
	v_cvt_pk_bf16_f32 v124, v168, v169
	v_cvt_pk_bf16_f32 v125, v170, v171
	v_lshl_add_u64 v[126:127], v[126:127], 0, v[154:155]
	global_store_dwordx4 v[126:127], v[122:125], off
	v_pk_mul_f32 v[178:179], v[168:169], v[168:169]
	v_pk_mul_f32 v[180:181], v[170:171], v[170:171]
	v_lshlrev_b32_e32 v122, 16, v138
	v_and_b32_e32 v123, 0xffff0000, v138
	v_pk_add_f32 v[118:119], v[118:119], v[122:123]
	v_lshlrev_b32_e32 v122, 16, v139
	v_and_b32_e32 v123, 0xffff0000, v139
	v_pk_add_f32 v[120:121], v[120:121], v[122:123]
	v_lshlrev_b32_e32 v122, 16, v140
	v_and_b32_e32 v123, 0xffff0000, v140
	v_pk_add_f32 v[122:123], v[114:115], v[122:123]
	v_lshlrev_b32_e32 v114, 16, v141
	v_and_b32_e32 v115, 0xffff0000, v141
	v_pk_add_f32 v[124:125], v[116:117], v[114:115]
	v_pk_mul_f32 v[114:115], v[118:119], v[118:119]
	v_pk_mul_f32 v[116:117], v[120:121], v[120:121]
	v_add_f32_e32 v114, v114, v115
	v_add_f32_e32 v116, v116, v117
	v_pk_mul_f32 v[176:177], v[128:129], v[128:129]
	v_pk_mul_f32 v[128:129], v[122:123], v[122:123]
	v_pk_mul_f32 v[138:139], v[124:125], v[124:125]
	v_add_f32_e32 v114, v114, v116
	v_add_f32_e32 v115, v180, v181
	v_add_f32_e32 v116, v178, v179
	v_add_f32_e32 v138, v138, v139
	v_add_f32_e32 v128, v128, v129
	v_add_f32_e32 v115, v116, v115
	v_add_f32_e32 v116, v176, v177
	v_add_f32_e32 v117, v174, v175
	v_add_f32_e32 v128, v128, v138
	v_add_f32_e32 v116, v117, v116
	v_add_f32_e32 v114, v114, v128
	v_add_f32_e32 v115, v116, v115
	v_add_f32_e32 v128, v115, v114
	v_cvt_pk_bf16_f32 v114, v118, v119
	v_cvt_pk_bf16_f32 v115, v120, v121
	v_cvt_pk_bf16_f32 v116, v122, v123
	v_cvt_pk_bf16_f32 v117, v124, v125
	global_store_dwordx4 v[126:127], v[114:117], off offset:256
	ds_bpermute_b32 v114, v167, v128
	s_waitcnt lgkmcnt(0)
	v_add_f32_e32 v114, v128, v114
	ds_bpermute_b32 v115, v166, v114
	s_and_saveexec_b64 s[0:1], vcc
	s_cbranch_execz .LBB0_243
	v_lshlrev_b64 v[116:117], 6, v[156:157]
	v_lshl_add_u64 v[116:117], s[24:25], 0, v[116:117]
	v_lshl_add_u64 v[116:117], s[84:85], 2, v[116:117]
	s_lshl_b32 s48, s44, 2
	v_lshl_add_u64 v[116:117], v[116:117], 0, s[48:49]
	s_waitcnt lgkmcnt(0)
	v_add_f32_e32 v114, v114, v115
	global_store_dword v[116:117], v114, off
.LBB0_243:
	s_or_b64 exec, exec, s[0:1]
	v_add_u32_e32 v122, 32, v156
	v_ashrrev_i32_e32 v123, 31, v122
	v_lshlrev_b64 v[124:125], 11, v[122:123]
	s_waitcnt lgkmcnt(0)
	v_lshl_add_u64 v[114:115], s[28:29], 0, v[124:125]
	v_lshl_add_u64 v[114:115], v[114:115], 0, v[154:155]
	global_load_dwordx4 v[118:121], v[114:115], off
	s_nop 0
	global_load_dwordx4 v[114:117], v[114:115], off offset:256
	s_waitcnt vmcnt(5)
; __device__ __forceinline__ unsigned pk2(float lo, float hi) { f32x2 v = {lo, hi}; bf16x2_t b = __builtin_convertvector(v, bf16x2_t); return __builtin_bit_cast(unsigned, b); }
; __device__ __forceinline__ float bflo(unsigned u) { return __uint_as_float(u << 16); }
; __device__ __forceinline__ float bfhi(unsigned u) { return __uint_as_float(u & 0xffff0000u); }
;     __device__ __forceinline__ void operator()(const Acc& acc, const Unit& u, int wr, int wc, int fr, int fq) const {
;     ...
;         for (int it = 0; it < 8; ++it) { const int ai = it >> 2, m = it & 3; const int row = row0 + ai * HALF + m * 16; float s = 0.f;
;             if (it + 1 < 8) { const bf16_t* np = Hin + (size_t)(row0 + ((it + 1) >> 2) * HALF + ((it + 1) & 3) * 16) * 1024 + col0;
; #pragma unroll
;                 for (int bj = 0; bj < 2; ++bj) hb[(it + 1) & 1][bj] = *(const u32x4*)(np + bj * HALF); }
; #pragma unroll
;             for (int bj = 0; bj < 2; ++bj) { const u32x4 hv = hb[it & 1][bj];
;                 f32x4 o0 = acc[ai][bj][m][0] * sc, o1 = acc[ai][bj][m][1] * sc;
;                 o0[0] += bflo(hv.x); o0[1] += bfhi(hv.x); o0[2] += bflo(hv.y); o0[3] += bfhi(hv.y); o1[0] += bflo(hv.z); o1[1] += bfhi(hv.z); o1[2] += bflo(hv.w); o1[3] += bfhi(hv.w);
;                 s += ((o0[0] * o0[0] + o0[1] * o0[1]) + (o0[2] * o0[2] + o0[3] * o0[3])) + ((o1[0] * o1[0] + o1[1] * o1[1]) + (o1[2] * o1[2] + o1[3] * o1[3]));
;                 if (Xout) { float* xp = Xout + (size_t)row * 1024 + col0 + bj * HALF; *(f32x4*)xp = o0; *(f32x4*)(xp + 4) = o1; }
;                 else { u32x4 w; w.x = pk2(o0[0], o0[1]); w.y = pk2(o0[2], o0[3]); w.z = pk2(o1[0], o1[1]); w.w = pk2(o1[2], o1[3]); *(u32x4*)(H + (size_t)row * 1024 + col0 + bj * HALF) = w; } }
;             s += __shfl_xor(s, 16); s += __shfl_xor(s, 32);
;             if (fq == 0) ssq[(size_t)row * 16 + u.pn * 4 + wc] = s;
;             asm volatile("" ::: "memory"); }
	v_lshlrev_b32_e32 v126, 16, v134
	v_and_b32_e32 v127, 0xffff0000, v134
	v_pk_add_f32 v[110:111], v[110:111], v[126:127]
	v_lshlrev_b32_e32 v126, 16, v135
	v_and_b32_e32 v127, 0xffff0000, v135
	v_pk_add_f32 v[112:113], v[112:113], v[126:127]
	v_lshlrev_b32_e32 v126, 16, v136
	v_and_b32_e32 v127, 0xffff0000, v136
	v_pk_add_f32 v[126:127], v[106:107], v[126:127]
	v_lshlrev_b32_e32 v106, 16, v137
	v_and_b32_e32 v107, 0xffff0000, v137
	v_pk_add_f32 v[128:129], v[108:109], v[106:107]
	v_pk_mul_f32 v[134:135], v[110:111], v[110:111]
	v_cvt_pk_bf16_f32 v106, v110, v111
	v_lshlrev_b32_e32 v110, 16, v130
	v_and_b32_e32 v111, 0xffff0000, v130
	v_pk_add_f32 v[102:103], v[102:103], v[110:111]
	v_lshlrev_b32_e32 v110, 16, v131
	v_and_b32_e32 v111, 0xffff0000, v131
	v_pk_add_f32 v[104:105], v[104:105], v[110:111]
	v_lshlrev_b32_e32 v110, 16, v132
	v_and_b32_e32 v111, 0xffff0000, v132
	v_pk_add_f32 v[110:111], v[98:99], v[110:111]
	v_lshlrev_b32_e32 v98, 16, v133
	v_and_b32_e32 v99, 0xffff0000, v133
	v_pk_mul_f32 v[136:137], v[112:113], v[112:113]
	v_cvt_pk_bf16_f32 v107, v112, v113
	v_pk_add_f32 v[112:113], v[100:101], v[98:99]
	v_pk_mul_f32 v[98:99], v[102:103], v[102:103]
	v_pk_mul_f32 v[100:101], v[104:105], v[104:105]
	v_pk_mul_f32 v[138:139], v[126:127], v[126:127]
	v_pk_mul_f32 v[140:141], v[128:129], v[128:129]
	v_add_f32_e32 v100, v100, v101
	v_add_f32_e32 v98, v98, v99
	v_cvt_pk_bf16_f32 v108, v126, v127
	v_cvt_pk_bf16_f32 v109, v128, v129
	v_pk_mul_f32 v[126:127], v[110:111], v[110:111]
	v_pk_mul_f32 v[128:129], v[112:113], v[112:113]
	v_add_f32_e32 v98, v98, v100
	v_add_f32_e32 v99, v140, v141
	v_add_f32_e32 v100, v138, v139
	v_add_f32_e32 v128, v128, v129
	v_add_f32_e32 v126, v126, v127
	v_add_f32_e32 v99, v100, v99
	v_add_f32_e32 v100, v136, v137
	v_add_f32_e32 v101, v134, v135
	v_add_f32_e32 v126, v126, v128
	v_add_f32_e32 v100, v101, v100
	v_add_f32_e32 v98, v98, v126
	v_add_f32_e32 v99, v100, v99
	v_add_f32_e32 v101, v99, v98
	ds_bpermute_b32 v128, v167, v101
	v_lshl_add_u64 v[98:99], s[36:37], 0, v[160:161]
	v_lshl_add_u64 v[126:127], v[98:99], 0, v[154:155]
	v_cvt_pk_bf16_f32 v100, v102, v103
	v_cvt_pk_bf16_f32 v102, v110, v111
	s_waitcnt lgkmcnt(0)
	v_add_f32_e32 v98, v101, v128
	ds_bpermute_b32 v99, v166, v98
	v_cvt_pk_bf16_f32 v101, v104, v105
	v_cvt_pk_bf16_f32 v103, v112, v113
	global_store_dwordx4 v[126:127], v[106:109], off
	global_store_dwordx4 v[126:127], v[100:103], off offset:256
	s_and_saveexec_b64 s[0:1], vcc
	s_cbranch_execz .LBB0_245
	v_lshlrev_b64 v[100:101], 6, v[158:159]
	v_lshl_add_u64 v[100:101], s[24:25], 0, v[100:101]
	v_lshl_add_u64 v[100:101], s[84:85], 2, v[100:101]
	s_lshl_b32 s48, s44, 2
	v_lshl_add_u64 v[100:101], v[100:101], 0, s[48:49]
	s_waitcnt lgkmcnt(0)
	v_add_f32_e32 v98, v98, v99
	global_store_dword v[100:101], v98, off
.LBB0_245:
	s_or_b64 exec, exec, s[0:1]
	v_add_u32_e32 v106, 48, v156
	v_ashrrev_i32_e32 v107, 31, v106
	v_lshlrev_b64 v[108:109], 11, v[106:107]
	s_waitcnt lgkmcnt(0)
	v_lshl_add_u64 v[98:99], s[28:29], 0, v[108:109]
	v_lshl_add_u64 v[98:99], v[98:99], 0, v[154:155]
	global_load_dwordx4 v[102:105], v[98:99], off
	s_nop 0
	global_load_dwordx4 v[98:101], v[98:99], off offset:256
	s_waitcnt vmcnt(2)
	v_lshlrev_b32_e32 v110, 16, v118
	v_and_b32_e32 v111, 0xffff0000, v118
	v_pk_add_f32 v[94:95], v[94:95], v[110:111]
	v_lshlrev_b32_e32 v110, 16, v119
	v_and_b32_e32 v111, 0xffff0000, v119
	v_pk_add_f32 v[96:97], v[96:97], v[110:111]
	v_lshlrev_b32_e32 v110, 16, v120
	v_and_b32_e32 v111, 0xffff0000, v120
	v_pk_add_f32 v[110:111], v[90:91], v[110:111]
	v_lshlrev_b32_e32 v90, 16, v121
	v_and_b32_e32 v91, 0xffff0000, v121
	v_pk_add_f32 v[112:113], v[92:93], v[90:91]
	v_pk_mul_f32 v[118:119], v[94:95], v[94:95]
	v_cvt_pk_bf16_f32 v90, v94, v95
	v_lshlrev_b32_e32 v94, 16, v114
	v_and_b32_e32 v95, 0xffff0000, v114
	v_pk_add_f32 v[86:87], v[86:87], v[94:95]
	v_lshlrev_b32_e32 v94, 16, v115
	v_and_b32_e32 v95, 0xffff0000, v115
	v_pk_add_f32 v[88:89], v[88:89], v[94:95]
	v_lshlrev_b32_e32 v94, 16, v116
	v_and_b32_e32 v95, 0xffff0000, v116
	v_pk_add_f32 v[94:95], v[82:83], v[94:95]
	v_lshlrev_b32_e32 v82, 16, v117
	v_and_b32_e32 v83, 0xffff0000, v117
	v_pk_mul_f32 v[120:121], v[96:97], v[96:97]
	v_cvt_pk_bf16_f32 v91, v96, v97
	v_pk_add_f32 v[96:97], v[84:85], v[82:83]
	v_pk_mul_f32 v[82:83], v[86:87], v[86:87]
	v_pk_mul_f32 v[84:85], v[88:89], v[88:89]
	v_pk_mul_f32 v[126:127], v[110:111], v[110:111]
	v_pk_mul_f32 v[128:129], v[112:113], v[112:113]
	v_add_f32_e32 v84, v84, v85
	v_add_f32_e32 v82, v82, v83
	v_cvt_pk_bf16_f32 v92, v110, v111
	v_cvt_pk_bf16_f32 v93, v112, v113
	v_pk_mul_f32 v[110:111], v[94:95], v[94:95]
	v_pk_mul_f32 v[112:113], v[96:97], v[96:97]
	v_add_f32_e32 v82, v82, v84
	v_add_f32_e32 v83, v128, v129
	v_add_f32_e32 v84, v126, v127
	v_add_f32_e32 v112, v112, v113
	v_add_f32_e32 v110, v110, v111
	v_add_f32_e32 v83, v84, v83
	v_add_f32_e32 v84, v120, v121
	v_add_f32_e32 v85, v118, v119
	v_add_f32_e32 v110, v110, v112
	v_add_f32_e32 v84, v85, v84
	v_add_f32_e32 v82, v82, v110
	v_add_f32_e32 v83, v84, v83
	v_add_f32_e32 v85, v83, v82
	ds_bpermute_b32 v112, v167, v85
	v_lshl_add_u64 v[82:83], s[36:37], 0, v[124:125]
	v_lshl_add_u64 v[110:111], v[82:83], 0, v[154:155]
	v_cvt_pk_bf16_f32 v84, v86, v87
	v_cvt_pk_bf16_f32 v86, v94, v95
	s_waitcnt lgkmcnt(0)
	v_add_f32_e32 v82, v85, v112
	ds_bpermute_b32 v83, v166, v82
	v_cvt_pk_bf16_f32 v85, v88, v89
	v_cvt_pk_bf16_f32 v87, v96, v97
	global_store_dwordx4 v[110:111], v[90:93], off
	global_store_dwordx4 v[110:111], v[84:87], off offset:256
	s_and_saveexec_b64 s[0:1], vcc
	s_cbranch_execz .LBB0_247
	v_lshlrev_b64 v[84:85], 6, v[122:123]
	v_lshl_add_u64 v[84:85], s[24:25], 0, v[84:85]
	v_lshl_add_u64 v[84:85], s[84:85], 2, v[84:85]
	s_lshl_b32 s48, s44, 2
	v_lshl_add_u64 v[84:85], v[84:85], 0, s[48:49]
	s_waitcnt lgkmcnt(0)
	v_add_f32_e32 v82, v82, v83
	global_store_dword v[84:85], v82, off
; __device__ __forceinline__ unsigned pk2(float lo, float hi) { f32x2 v = {lo, hi}; bf16x2_t b = __builtin_convertvector(v, bf16x2_t); return __builtin_bit_cast(unsigned, b); }
; __device__ __forceinline__ float bflo(unsigned u) { return __uint_as_float(u << 16); }
; __device__ __forceinline__ float bfhi(unsigned u) { return __uint_as_float(u & 0xffff0000u); }
;     __device__ __forceinline__ void operator()(const Acc& acc, const Unit& u, int wr, int wc, int fr, int fq) const {
;     ...
;         for (int it = 0; it < 8; ++it) { const int ai = it >> 2, m = it & 3; const int row = row0 + ai * HALF + m * 16; float s = 0.f;
;             if (it + 1 < 8) { const bf16_t* np = Hin + (size_t)(row0 + ((it + 1) >> 2) * HALF + ((it + 1) & 3) * 16) * 1024 + col0;
; #pragma unroll
;                 for (int bj = 0; bj < 2; ++bj) hb[(it + 1) & 1][bj] = *(const u32x4*)(np + bj * HALF); }
; #pragma unroll
;             for (int bj = 0; bj < 2; ++bj) { const u32x4 hv = hb[it & 1][bj];
;                 f32x4 o0 = acc[ai][bj][m][0] * sc, o1 = acc[ai][bj][m][1] * sc;
;                 o0[0] += bflo(hv.x); o0[1] += bfhi(hv.x); o0[2] += bflo(hv.y); o0[3] += bfhi(hv.y); o1[0] += bflo(hv.z); o1[1] += bfhi(hv.z); o1[2] += bflo(hv.w); o1[3] += bfhi(hv.w);
;                 s += ((o0[0] * o0[0] + o0[1] * o0[1]) + (o0[2] * o0[2] + o0[3] * o0[3])) + ((o1[0] * o1[0] + o1[1] * o1[1]) + (o1[2] * o1[2] + o1[3] * o1[3]));
;                 if (Xout) { float* xp = Xout + (size_t)row * 1024 + col0 + bj * HALF; *(f32x4*)xp = o0; *(f32x4*)(xp + 4) = o1; }
;                 else { u32x4 w; w.x = pk2(o0[0], o0[1]); w.y = pk2(o0[2], o0[3]); w.z = pk2(o1[0], o1[1]); w.w = pk2(o1[2], o1[3]); *(u32x4*)(H + (size_t)row * 1024 + col0 + bj * HALF) = w; } }
;             s += __shfl_xor(s, 16); s += __shfl_xor(s, 32);
;             if (fq == 0) ssq[(size_t)row * 16 + u.pn * 4 + wc] = s;
;             asm volatile("" ::: "memory"); }
.LBB0_247:
	s_or_b64 exec, exec, s[0:1]
	v_add_u32_e32 v90, 0x80, v156
	v_ashrrev_i32_e32 v91, 31, v90
	v_lshlrev_b64 v[92:93], 11, v[90:91]
	s_waitcnt lgkmcnt(0)
	v_lshl_add_u64 v[82:83], s[28:29], 0, v[92:93]
	v_lshl_add_u64 v[82:83], v[82:83], 0, v[154:155]
	global_load_dwordx4 v[86:89], v[82:83], off
	s_nop 0
	global_load_dwordx4 v[82:85], v[82:83], off offset:256
	s_waitcnt vmcnt(5)
	v_lshlrev_b32_e32 v94, 16, v102
	v_and_b32_e32 v95, 0xffff0000, v102
	v_pk_add_f32 v[78:79], v[78:79], v[94:95]
	v_lshlrev_b32_e32 v94, 16, v103
	v_and_b32_e32 v95, 0xffff0000, v103
	v_pk_add_f32 v[80:81], v[80:81], v[94:95]
	v_lshlrev_b32_e32 v94, 16, v104
	v_and_b32_e32 v95, 0xffff0000, v104
	v_pk_add_f32 v[94:95], v[74:75], v[94:95]
	v_lshlrev_b32_e32 v74, 16, v105
	v_and_b32_e32 v75, 0xffff0000, v105
	v_pk_add_f32 v[96:97], v[76:77], v[74:75]
	v_pk_mul_f32 v[102:103], v[78:79], v[78:79]
	v_cvt_pk_bf16_f32 v74, v78, v79
	v_lshlrev_b32_e32 v78, 16, v98
	v_and_b32_e32 v79, 0xffff0000, v98
	v_pk_add_f32 v[70:71], v[70:71], v[78:79]
	v_lshlrev_b32_e32 v78, 16, v99
	v_and_b32_e32 v79, 0xffff0000, v99
	v_pk_add_f32 v[72:73], v[72:73], v[78:79]
	v_lshlrev_b32_e32 v78, 16, v100
	v_and_b32_e32 v79, 0xffff0000, v100
	v_pk_add_f32 v[78:79], v[66:67], v[78:79]
	v_lshlrev_b32_e32 v66, 16, v101
	v_and_b32_e32 v67, 0xffff0000, v101
	v_pk_mul_f32 v[104:105], v[80:81], v[80:81]
	v_cvt_pk_bf16_f32 v75, v80, v81
	v_pk_add_f32 v[80:81], v[68:69], v[66:67]
	v_pk_mul_f32 v[66:67], v[70:71], v[70:71]
	v_pk_mul_f32 v[68:69], v[72:73], v[72:73]
	v_pk_mul_f32 v[110:111], v[94:95], v[94:95]
	v_pk_mul_f32 v[112:113], v[96:97], v[96:97]
	v_add_f32_e32 v68, v68, v69
	v_add_f32_e32 v66, v66, v67
	v_cvt_pk_bf16_f32 v76, v94, v95
	v_cvt_pk_bf16_f32 v77, v96, v97
	v_pk_mul_f32 v[94:95], v[78:79], v[78:79]
	v_pk_mul_f32 v[96:97], v[80:81], v[80:81]
	v_add_f32_e32 v66, v66, v68
	v_add_f32_e32 v67, v112, v113
	v_add_f32_e32 v68, v110, v111
	v_add_f32_e32 v96, v96, v97
	v_add_f32_e32 v94, v94, v95
	v_add_f32_e32 v67, v68, v67
	v_add_f32_e32 v68, v104, v105
	v_add_f32_e32 v69, v102, v103
	v_add_f32_e32 v94, v94, v96
	v_add_f32_e32 v68, v69, v68
	v_add_f32_e32 v66, v66, v94
	v_add_f32_e32 v67, v68, v67
	v_add_f32_e32 v69, v67, v66
	ds_bpermute_b32 v96, v167, v69
	v_lshl_add_u64 v[66:67], s[36:37], 0, v[108:109]
	v_lshl_add_u64 v[94:95], v[66:67], 0, v[154:155]
	v_cvt_pk_bf16_f32 v68, v70, v71
	v_cvt_pk_bf16_f32 v70, v78, v79
	s_waitcnt lgkmcnt(0)
	v_add_f32_e32 v66, v69, v96
	ds_bpermute_b32 v67, v166, v66
	v_cvt_pk_bf16_f32 v69, v72, v73
	v_cvt_pk_bf16_f32 v71, v80, v81
	global_store_dwordx4 v[94:95], v[74:77], off
	global_store_dwordx4 v[94:95], v[68:71], off offset:256
	s_and_saveexec_b64 s[0:1], vcc
	s_cbranch_execz .LBB0_249
	v_lshlrev_b64 v[68:69], 6, v[106:107]
	v_lshl_add_u64 v[68:69], s[24:25], 0, v[68:69]
	v_lshl_add_u64 v[68:69], s[84:85], 2, v[68:69]
	s_lshl_b32 s48, s44, 2
	v_lshl_add_u64 v[68:69], v[68:69], 0, s[48:49]
	s_waitcnt lgkmcnt(0)
	v_add_f32_e32 v66, v66, v67
	global_store_dword v[68:69], v66, off
.LBB0_249:
	s_or_b64 exec, exec, s[0:1]
	v_add_u32_e32 v74, 0x90, v156
	v_ashrrev_i32_e32 v75, 31, v74
	v_lshlrev_b64 v[76:77], 11, v[74:75]
	s_waitcnt lgkmcnt(0)
	v_lshl_add_u64 v[66:67], s[28:29], 0, v[76:77]
	v_lshl_add_u64 v[66:67], v[66:67], 0, v[154:155]
	global_load_dwordx4 v[70:73], v[66:67], off
	s_nop 0
	global_load_dwordx4 v[66:69], v[66:67], off offset:256
	s_waitcnt vmcnt(2)
	v_lshlrev_b32_e32 v78, 16, v86
	v_and_b32_e32 v79, 0xffff0000, v86
	v_pk_add_f32 v[62:63], v[62:63], v[78:79]
	v_lshlrev_b32_e32 v78, 16, v87
	v_and_b32_e32 v79, 0xffff0000, v87
	v_pk_add_f32 v[64:65], v[64:65], v[78:79]
	v_lshlrev_b32_e32 v78, 16, v88
	v_and_b32_e32 v79, 0xffff0000, v88
	v_pk_add_f32 v[78:79], v[58:59], v[78:79]
	v_lshlrev_b32_e32 v58, 16, v89
	v_and_b32_e32 v59, 0xffff0000, v89
	v_pk_add_f32 v[80:81], v[60:61], v[58:59]
	v_pk_mul_f32 v[86:87], v[62:63], v[62:63]
	v_cvt_pk_bf16_f32 v58, v62, v63
	v_lshlrev_b32_e32 v62, 16, v82
	v_and_b32_e32 v63, 0xffff0000, v82
	v_pk_add_f32 v[54:55], v[54:55], v[62:63]
	v_lshlrev_b32_e32 v62, 16, v83
	v_and_b32_e32 v63, 0xffff0000, v83
	v_pk_add_f32 v[56:57], v[56:57], v[62:63]
	v_lshlrev_b32_e32 v62, 16, v84
	v_and_b32_e32 v63, 0xffff0000, v84
	v_pk_add_f32 v[62:63], v[50:51], v[62:63]
	v_lshlrev_b32_e32 v50, 16, v85
	v_and_b32_e32 v51, 0xffff0000, v85
	v_pk_mul_f32 v[88:89], v[64:65], v[64:65]
	v_cvt_pk_bf16_f32 v59, v64, v65
	v_pk_add_f32 v[64:65], v[52:53], v[50:51]
	v_pk_mul_f32 v[50:51], v[54:55], v[54:55]
	v_pk_mul_f32 v[52:53], v[56:57], v[56:57]
	v_pk_mul_f32 v[94:95], v[78:79], v[78:79]
	v_pk_mul_f32 v[96:97], v[80:81], v[80:81]
	v_add_f32_e32 v52, v52, v53
	v_add_f32_e32 v50, v50, v51
	v_cvt_pk_bf16_f32 v60, v78, v79
	v_cvt_pk_bf16_f32 v61, v80, v81
	v_pk_mul_f32 v[78:79], v[62:63], v[62:63]
	v_pk_mul_f32 v[80:81], v[64:65], v[64:65]
	v_add_f32_e32 v50, v50, v52
	v_add_f32_e32 v51, v96, v97
	v_add_f32_e32 v52, v94, v95
	v_add_f32_e32 v80, v80, v81
	v_add_f32_e32 v78, v78, v79
	v_add_f32_e32 v51, v52, v51
	v_add_f32_e32 v52, v88, v89
	v_add_f32_e32 v53, v86, v87
	v_add_f32_e32 v78, v78, v80
	v_add_f32_e32 v52, v53, v52
	v_add_f32_e32 v50, v50, v78
	v_add_f32_e32 v51, v52, v51
	v_add_f32_e32 v53, v51, v50
	ds_bpermute_b32 v80, v167, v53
	v_lshl_add_u64 v[50:51], s[36:37], 0, v[92:93]
	v_lshl_add_u64 v[78:79], v[50:51], 0, v[154:155]
	v_cvt_pk_bf16_f32 v52, v54, v55
	v_cvt_pk_bf16_f32 v54, v62, v63
	s_waitcnt lgkmcnt(0)
	v_add_f32_e32 v50, v53, v80
	ds_bpermute_b32 v51, v166, v50
	v_cvt_pk_bf16_f32 v53, v56, v57
	v_cvt_pk_bf16_f32 v55, v64, v65
	global_store_dwordx4 v[78:79], v[58:61], off
	global_store_dwordx4 v[78:79], v[52:55], off offset:256
	s_and_saveexec_b64 s[0:1], vcc
	s_cbranch_execz .LBB0_251
	v_lshlrev_b64 v[52:53], 6, v[90:91]
	v_lshl_add_u64 v[52:53], s[24:25], 0, v[52:53]
	v_lshl_add_u64 v[52:53], s[84:85], 2, v[52:53]
	s_lshl_b32 s48, s44, 2
	v_lshl_add_u64 v[52:53], v[52:53], 0, s[48:49]
	s_waitcnt lgkmcnt(0)
	v_add_f32_e32 v50, v50, v51
	global_store_dword v[52:53], v50, off
; __device__ __forceinline__ unsigned pk2(float lo, float hi) { f32x2 v = {lo, hi}; bf16x2_t b = __builtin_convertvector(v, bf16x2_t); return __builtin_bit_cast(unsigned, b); }
; __device__ __forceinline__ float bflo(unsigned u) { return __uint_as_float(u << 16); }
; __device__ __forceinline__ float bfhi(unsigned u) { return __uint_as_float(u & 0xffff0000u); }
;     __device__ __forceinline__ void operator()(const Acc& acc, const Unit& u, int wr, int wc, int fr, int fq) const {
;     ...
;         for (int it = 0; it < 8; ++it) { const int ai = it >> 2, m = it & 3; const int row = row0 + ai * HALF + m * 16; float s = 0.f;
;             if (it + 1 < 8) { const bf16_t* np = Hin + (size_t)(row0 + ((it + 1) >> 2) * HALF + ((it + 1) & 3) * 16) * 1024 + col0;
; #pragma unroll
;                 for (int bj = 0; bj < 2; ++bj) hb[(it + 1) & 1][bj] = *(const u32x4*)(np + bj * HALF); }
; #pragma unroll
;             for (int bj = 0; bj < 2; ++bj) { const u32x4 hv = hb[it & 1][bj];
;                 f32x4 o0 = acc[ai][bj][m][0] * sc, o1 = acc[ai][bj][m][1] * sc;
;                 o0[0] += bflo(hv.x); o0[1] += bfhi(hv.x); o0[2] += bflo(hv.y); o0[3] += bfhi(hv.y); o1[0] += bflo(hv.z); o1[1] += bfhi(hv.z); o1[2] += bflo(hv.w); o1[3] += bfhi(hv.w);
;                 s += ((o0[0] * o0[0] + o0[1] * o0[1]) + (o0[2] * o0[2] + o0[3] * o0[3])) + ((o1[0] * o1[0] + o1[1] * o1[1]) + (o1[2] * o1[2] + o1[3] * o1[3]));
;                 if (Xout) { float* xp = Xout + (size_t)row * 1024 + col0 + bj * HALF; *(f32x4*)xp = o0; *(f32x4*)(xp + 4) = o1; }
;                 else { u32x4 w; w.x = pk2(o0[0], o0[1]); w.y = pk2(o0[2], o0[3]); w.z = pk2(o1[0], o1[1]); w.w = pk2(o1[2], o1[3]); *(u32x4*)(H + (size_t)row * 1024 + col0 + bj * HALF) = w; } }
;             s += __shfl_xor(s, 16); s += __shfl_xor(s, 32);
;             if (fq == 0) ssq[(size_t)row * 16 + u.pn * 4 + wc] = s;
;             asm volatile("" ::: "memory"); }
.LBB0_251:
	s_or_b64 exec, exec, s[0:1]
	v_add_u32_e32 v58, 0xa0, v156
	v_ashrrev_i32_e32 v59, 31, v58
	v_lshlrev_b64 v[60:61], 11, v[58:59]
	s_waitcnt lgkmcnt(0)
	v_lshl_add_u64 v[50:51], s[28:29], 0, v[60:61]
	v_lshl_add_u64 v[50:51], v[50:51], 0, v[154:155]
	global_load_dwordx4 v[54:57], v[50:51], off
	s_nop 0
	global_load_dwordx4 v[50:53], v[50:51], off offset:256
	s_waitcnt vmcnt(5)
	v_lshlrev_b32_e32 v62, 16, v70
	v_and_b32_e32 v63, 0xffff0000, v70
	v_pk_add_f32 v[46:47], v[46:47], v[62:63]
	v_lshlrev_b32_e32 v62, 16, v71
	v_and_b32_e32 v63, 0xffff0000, v71
	v_pk_add_f32 v[48:49], v[48:49], v[62:63]
	v_lshlrev_b32_e32 v62, 16, v72
	v_and_b32_e32 v63, 0xffff0000, v72
	v_pk_add_f32 v[62:63], v[42:43], v[62:63]
	v_lshlrev_b32_e32 v42, 16, v73
	v_and_b32_e32 v43, 0xffff0000, v73
	v_pk_add_f32 v[64:65], v[44:45], v[42:43]
	v_pk_mul_f32 v[70:71], v[46:47], v[46:47]
	v_cvt_pk_bf16_f32 v42, v46, v47
	v_lshlrev_b32_e32 v46, 16, v66
	v_and_b32_e32 v47, 0xffff0000, v66
	v_pk_add_f32 v[38:39], v[38:39], v[46:47]
	v_lshlrev_b32_e32 v46, 16, v67
	v_and_b32_e32 v47, 0xffff0000, v67
	v_pk_add_f32 v[40:41], v[40:41], v[46:47]
	v_lshlrev_b32_e32 v46, 16, v68
	v_and_b32_e32 v47, 0xffff0000, v68
	v_pk_add_f32 v[46:47], v[34:35], v[46:47]
	v_lshlrev_b32_e32 v34, 16, v69
	v_and_b32_e32 v35, 0xffff0000, v69
	v_pk_mul_f32 v[72:73], v[48:49], v[48:49]
	v_cvt_pk_bf16_f32 v43, v48, v49
	v_pk_add_f32 v[48:49], v[36:37], v[34:35]
	v_pk_mul_f32 v[34:35], v[38:39], v[38:39]
	v_pk_mul_f32 v[36:37], v[40:41], v[40:41]
	v_pk_mul_f32 v[78:79], v[62:63], v[62:63]
	v_pk_mul_f32 v[80:81], v[64:65], v[64:65]
	v_add_f32_e32 v36, v36, v37
	v_add_f32_e32 v34, v34, v35
	v_cvt_pk_bf16_f32 v44, v62, v63
	v_cvt_pk_bf16_f32 v45, v64, v65
	v_pk_mul_f32 v[62:63], v[46:47], v[46:47]
	v_pk_mul_f32 v[64:65], v[48:49], v[48:49]
	v_add_f32_e32 v34, v34, v36
	v_add_f32_e32 v35, v80, v81
	v_add_f32_e32 v36, v78, v79
	v_add_f32_e32 v64, v64, v65
	v_add_f32_e32 v62, v62, v63
	v_add_f32_e32 v35, v36, v35
	v_add_f32_e32 v36, v72, v73
	v_add_f32_e32 v37, v70, v71
	v_add_f32_e32 v62, v62, v64
	v_add_f32_e32 v36, v37, v36
	v_add_f32_e32 v34, v34, v62
	v_add_f32_e32 v35, v36, v35
	v_add_f32_e32 v37, v35, v34
	ds_bpermute_b32 v64, v167, v37
	v_lshl_add_u64 v[34:35], s[36:37], 0, v[76:77]
	v_lshl_add_u64 v[62:63], v[34:35], 0, v[154:155]
	v_cvt_pk_bf16_f32 v36, v38, v39
	v_cvt_pk_bf16_f32 v38, v46, v47
	s_waitcnt lgkmcnt(0)
	v_add_f32_e32 v34, v37, v64
	ds_bpermute_b32 v35, v166, v34
	v_cvt_pk_bf16_f32 v37, v40, v41
	v_cvt_pk_bf16_f32 v39, v48, v49
	global_store_dwordx4 v[62:63], v[42:45], off
	global_store_dwordx4 v[62:63], v[36:39], off offset:256
	s_and_saveexec_b64 s[0:1], vcc
	s_cbranch_execz .LBB0_253
	v_lshlrev_b64 v[36:37], 6, v[74:75]
	v_lshl_add_u64 v[36:37], s[24:25], 0, v[36:37]
	v_lshl_add_u64 v[36:37], s[84:85], 2, v[36:37]
	s_lshl_b32 s48, s44, 2
	v_lshl_add_u64 v[36:37], v[36:37], 0, s[48:49]
	s_waitcnt lgkmcnt(0)
	v_add_f32_e32 v34, v34, v35
	global_store_dword v[36:37], v34, off
; __device__ __forceinline__ unsigned pk2(float lo, float hi) { f32x2 v = {lo, hi}; bf16x2_t b = __builtin_convertvector(v, bf16x2_t); return __builtin_bit_cast(unsigned, b); }
; __device__ __forceinline__ float bflo(unsigned u) { return __uint_as_float(u << 16); }
; __device__ __forceinline__ float bfhi(unsigned u) { return __uint_as_float(u & 0xffff0000u); }
;     __device__ __forceinline__ void operator()(const Acc& acc, const Unit& u, int wr, int wc, int fr, int fq) const {
;     ...
;         for (int it = 0; it < 8; ++it) { const int ai = it >> 2, m = it & 3; const int row = row0 + ai * HALF + m * 16; float s = 0.f;
;             if (it + 1 < 8) { const bf16_t* np = Hin + (size_t)(row0 + ((it + 1) >> 2) * HALF + ((it + 1) & 3) * 16) * 1024 + col0;
; #pragma unroll
;                 for (int bj = 0; bj < 2; ++bj) hb[(it + 1) & 1][bj] = *(const u32x4*)(np + bj * HALF); }
; #pragma unroll
;             for (int bj = 0; bj < 2; ++bj) { const u32x4 hv = hb[it & 1][bj];
;                 f32x4 o0 = acc[ai][bj][m][0] * sc, o1 = acc[ai][bj][m][1] * sc;
;                 o0[0] += bflo(hv.x); o0[1] += bfhi(hv.x); o0[2] += bflo(hv.y); o0[3] += bfhi(hv.y); o1[0] += bflo(hv.z); o1[1] += bfhi(hv.z); o1[2] += bflo(hv.w); o1[3] += bfhi(hv.w);
;                 s += ((o0[0] * o0[0] + o0[1] * o0[1]) + (o0[2] * o0[2] + o0[3] * o0[3])) + ((o1[0] * o1[0] + o1[1] * o1[1]) + (o1[2] * o1[2] + o1[3] * o1[3]));
;                 if (Xout) { float* xp = Xout + (size_t)row * 1024 + col0 + bj * HALF; *(f32x4*)xp = o0; *(f32x4*)(xp + 4) = o1; }
;                 else { u32x4 w; w.x = pk2(o0[0], o0[1]); w.y = pk2(o0[2], o0[3]); w.z = pk2(o1[0], o1[1]); w.w = pk2(o1[2], o1[3]); *(u32x4*)(H + (size_t)row * 1024 + col0 + bj * HALF) = w; } }
;             s += __shfl_xor(s, 16); s += __shfl_xor(s, 32);
;             if (fq == 0) ssq[(size_t)row * 16 + u.pn * 4 + wc] = s;
;             asm volatile("" ::: "memory"); }
.LBB0_253:
	s_or_b64 exec, exec, s[0:1]
	v_add_u32_e32 v42, 0xb0, v156
	v_ashrrev_i32_e32 v43, 31, v42
	v_lshlrev_b64 v[44:45], 11, v[42:43]
	s_waitcnt lgkmcnt(0)
	v_lshl_add_u64 v[34:35], s[28:29], 0, v[44:45]
	v_lshl_add_u64 v[34:35], v[34:35], 0, v[154:155]
	global_load_dwordx4 v[38:41], v[34:35], off
	s_nop 0
	global_load_dwordx4 v[34:37], v[34:35], off offset:256
	s_waitcnt vmcnt(2)
	v_lshlrev_b32_e32 v46, 16, v54
	v_and_b32_e32 v47, 0xffff0000, v54
	v_pk_add_f32 v[30:31], v[30:31], v[46:47]
	v_lshlrev_b32_e32 v46, 16, v55
	v_and_b32_e32 v47, 0xffff0000, v55
	v_pk_add_f32 v[32:33], v[32:33], v[46:47]
	v_lshlrev_b32_e32 v46, 16, v56
	v_and_b32_e32 v47, 0xffff0000, v56
	v_pk_add_f32 v[46:47], v[26:27], v[46:47]
	v_lshlrev_b32_e32 v26, 16, v57
	v_and_b32_e32 v27, 0xffff0000, v57
	v_pk_add_f32 v[48:49], v[28:29], v[26:27]
	v_pk_mul_f32 v[54:55], v[30:31], v[30:31]
	v_cvt_pk_bf16_f32 v26, v30, v31
	v_lshlrev_b32_e32 v30, 16, v50
	v_and_b32_e32 v31, 0xffff0000, v50
	v_pk_add_f32 v[22:23], v[22:23], v[30:31]
	v_lshlrev_b32_e32 v30, 16, v51
	v_and_b32_e32 v31, 0xffff0000, v51
	v_pk_add_f32 v[24:25], v[24:25], v[30:31]
	v_lshlrev_b32_e32 v30, 16, v52
	v_and_b32_e32 v31, 0xffff0000, v52
	v_pk_add_f32 v[30:31], v[18:19], v[30:31]
	v_lshlrev_b32_e32 v18, 16, v53
	v_and_b32_e32 v19, 0xffff0000, v53
	v_pk_mul_f32 v[56:57], v[32:33], v[32:33]
	v_cvt_pk_bf16_f32 v27, v32, v33
	v_pk_add_f32 v[32:33], v[20:21], v[18:19]
	v_pk_mul_f32 v[18:19], v[22:23], v[22:23]
	v_pk_mul_f32 v[20:21], v[24:25], v[24:25]
	v_pk_mul_f32 v[62:63], v[46:47], v[46:47]
	v_pk_mul_f32 v[64:65], v[48:49], v[48:49]
	v_add_f32_e32 v20, v20, v21
	v_add_f32_e32 v18, v18, v19
	v_cvt_pk_bf16_f32 v28, v46, v47
	v_cvt_pk_bf16_f32 v29, v48, v49
	v_pk_mul_f32 v[46:47], v[30:31], v[30:31]
	v_pk_mul_f32 v[48:49], v[32:33], v[32:33]
	v_add_f32_e32 v18, v18, v20
	v_add_f32_e32 v19, v64, v65
	v_add_f32_e32 v20, v62, v63
	v_add_f32_e32 v48, v48, v49
	v_add_f32_e32 v46, v46, v47
	v_add_f32_e32 v19, v20, v19
	v_add_f32_e32 v20, v56, v57
	v_add_f32_e32 v21, v54, v55
	v_add_f32_e32 v46, v46, v48
	v_add_f32_e32 v20, v21, v20
	v_add_f32_e32 v18, v18, v46
	v_add_f32_e32 v19, v20, v19
	v_add_f32_e32 v21, v19, v18
	ds_bpermute_b32 v48, v167, v21
	v_lshl_add_u64 v[18:19], s[36:37], 0, v[60:61]
	v_lshl_add_u64 v[46:47], v[18:19], 0, v[154:155]
	v_cvt_pk_bf16_f32 v20, v22, v23
	v_cvt_pk_bf16_f32 v22, v30, v31
	s_waitcnt lgkmcnt(0)
	v_add_f32_e32 v18, v21, v48
	ds_bpermute_b32 v19, v166, v18
	v_cvt_pk_bf16_f32 v21, v24, v25
	v_cvt_pk_bf16_f32 v23, v32, v33
	global_store_dwordx4 v[46:47], v[26:29], off
	global_store_dwordx4 v[46:47], v[20:23], off offset:256
	s_and_saveexec_b64 s[0:1], vcc
	s_cbranch_execz .LBB0_255
	v_lshlrev_b64 v[20:21], 6, v[58:59]
	v_lshl_add_u64 v[20:21], s[24:25], 0, v[20:21]
	v_lshl_add_u64 v[20:21], s[84:85], 2, v[20:21]
	s_lshl_b32 s48, s44, 2
	v_lshl_add_u64 v[20:21], v[20:21], 0, s[48:49]
	s_waitcnt lgkmcnt(0)
	v_add_f32_e32 v18, v18, v19
	global_store_dword v[20:21], v18, off
.LBB0_255:
	s_or_b64 exec, exec, s[0:1]
	s_waitcnt vmcnt(3)
	v_lshlrev_b32_e32 v18, 16, v38
	s_waitcnt lgkmcnt(0)
	v_and_b32_e32 v19, 0xffff0000, v38
	v_pk_add_f32 v[14:15], v[14:15], v[18:19]
	v_lshlrev_b32_e32 v18, 16, v39
	v_and_b32_e32 v19, 0xffff0000, v39
	v_pk_add_f32 v[16:17], v[16:17], v[18:19]
	v_lshlrev_b32_e32 v18, 16, v40
	v_and_b32_e32 v19, 0xffff0000, v40
	v_pk_add_f32 v[18:19], v[10:11], v[18:19]
	v_lshlrev_b32_e32 v10, 16, v41
	v_and_b32_e32 v11, 0xffff0000, v41
	v_pk_add_f32 v[20:21], v[12:13], v[10:11]
	v_pk_mul_f32 v[22:23], v[14:15], v[14:15]
	v_cvt_pk_bf16_f32 v10, v14, v15
	v_lshlrev_b32_e32 v14, 16, v34
	v_and_b32_e32 v15, 0xffff0000, v34
	v_pk_add_f32 v[6:7], v[6:7], v[14:15]
	v_lshlrev_b32_e32 v14, 16, v35
	v_and_b32_e32 v15, 0xffff0000, v35
	v_pk_add_f32 v[8:9], v[8:9], v[14:15]
	v_lshlrev_b32_e32 v14, 16, v36
	v_and_b32_e32 v15, 0xffff0000, v36
	v_pk_add_f32 v[14:15], v[2:3], v[14:15]
	v_lshlrev_b32_e32 v2, 16, v37
	v_and_b32_e32 v3, 0xffff0000, v37
	v_pk_mul_f32 v[24:25], v[16:17], v[16:17]
	v_cvt_pk_bf16_f32 v11, v16, v17
	v_pk_add_f32 v[16:17], v[4:5], v[2:3]
	v_pk_mul_f32 v[2:3], v[6:7], v[6:7]
	v_pk_mul_f32 v[4:5], v[8:9], v[8:9]
	v_pk_mul_f32 v[26:27], v[18:19], v[18:19]
	v_pk_mul_f32 v[28:29], v[20:21], v[20:21]
	v_add_f32_e32 v4, v4, v5
	v_add_f32_e32 v2, v2, v3
	v_cvt_pk_bf16_f32 v12, v18, v19
	v_cvt_pk_bf16_f32 v13, v20, v21
	v_pk_mul_f32 v[18:19], v[14:15], v[14:15]
	v_pk_mul_f32 v[20:21], v[16:17], v[16:17]
	v_add_f32_e32 v2, v2, v4
	v_add_f32_e32 v3, v28, v29
	v_add_f32_e32 v4, v26, v27
	v_add_f32_e32 v20, v20, v21
	v_add_f32_e32 v18, v18, v19
	v_add_f32_e32 v3, v4, v3
	v_add_f32_e32 v4, v24, v25
	v_add_f32_e32 v5, v22, v23
	v_add_f32_e32 v18, v18, v20
	v_add_f32_e32 v4, v5, v4
	v_add_f32_e32 v2, v2, v18
	v_add_f32_e32 v3, v4, v3
	v_add_f32_e32 v5, v3, v2
	ds_bpermute_b32 v20, v167, v5
	v_lshl_add_u64 v[2:3], s[36:37], 0, v[44:45]
	v_lshl_add_u64 v[18:19], v[152:153], 1, v[2:3]
	v_cvt_pk_bf16_f32 v4, v6, v7
	s_waitcnt lgkmcnt(0)
	v_add_f32_e32 v2, v5, v20
	ds_bpermute_b32 v3, v166, v2
	v_cvt_pk_bf16_f32 v5, v8, v9
	v_cvt_pk_bf16_f32 v6, v14, v15
	v_cvt_pk_bf16_f32 v7, v16, v17
	global_store_dwordx4 v[18:19], v[10:13], off
	global_store_dwordx4 v[18:19], v[4:7], off offset:256
	s_and_saveexec_b64 s[0:1], vcc
	s_cbranch_execz .LBB0_257
	v_lshlrev_b64 v[4:5], 6, v[42:43]
	v_lshl_add_u64 v[4:5], s[24:25], 0, v[4:5]
	v_lshl_add_u64 v[4:5], s[84:85], 2, v[4:5]
	s_lshl_b32 s48, s44, 2
	v_lshl_add_u64 v[4:5], v[4:5], 0, s[48:49]
	s_waitcnt lgkmcnt(0)
	v_add_f32_e32 v2, v2, v3
	global_store_dword v[4:5], v2, off
